# combined trims: hoisted helper invariants, Y-first ordering with y stores and decay-factor loads under the SA-half MFMAs, X-phase fillers capped at 3 per gap
# speedup vs baseline: 1.0186x; 1.0093x over previous
.Lmy_ck_nz:
	s_mov_b32 s100, 0xe000
	s_cmp_eq_u32 s23, 0
	s_cselect_b32 s100, 0x1c000, s100
	s_mov_b32 s101, 0x12e00
	s_cselect_b32 s101, 0x22100, s101
	s_lshl_b32 s96, s23, 13
	s_add_i32 s97, s96, 0x18000
	s_add_i32 s96, s96, 0xa000
	v_add_u32_e32 v225, s100, v1
	v_add_u32_e32 v236, s100, v0
	v_add_u32_e32 v34, s100, v10
	v_add_u32_e32 v226, s100, v2
	v_add_u32_e32 v227, s100, v3
	v_add_u32_e32 v228, s100, v4
	v_add_u32_e32 v229, s100, v5
	v_add_u32_e32 v237, s100, v6
	v_add_u32_e32 v238, s100, v7
	v_add_u32_e32 v230, s96, v8
	v_add_u32_e32 v239, s96, v9
	v_add_u32_e32 v231, s97, v8
	v_add_u32_e32 v26, s101, v1
	v_add_u32_e32 v27, s101, v0
	v_add_u32_e32 v35, s101, v10
	v_add_u32_e32 v28, s101, v2
	v_add_u32_e32 v29, s101, v3
	v_add_u32_e32 v30, s101, v4
	v_add_u32_e32 v31, s101, v5
	v_add_u32_e32 v32, s101, v6
	v_add_u32_e32 v33, s101, v7
	ds_read_b64 v[80:81], v237
	ds_read_b64 v[82:83], v238
	ds_read_b32 v36, v239
	ds_read_b32 v37, v239 offset:256
	ds_read_b128 v[88:91], v225
	ds_read_b128 v[92:95], v225 offset:1024
	ds_read_b128 v[96:99], v225 offset:2048
	ds_read_b128 v[100:103], v225 offset:3072
	ds_read_b32 v104, v227 offset:4
	ds_read_b32 v105, v227 offset:76
	ds_read_b64 v[106:107], v227 offset:8
	ds_read_b64 v[108:109], v227 offset:40
	ds_read_b32 v126, v229 offset:4
	ds_read_b32 v127, v229 offset:76
	ds_read_b64 v[128:129], v229 offset:8
	ds_read_b64 v[130:131], v229 offset:40
	ds_read_b64 v[110:111], v228
	ds_read_b64 v[112:113], v228 offset:32
	ds_read_b64 v[114:115], v228 offset:64
	ds_read_b64 v[116:117], v228 offset:96
	ds_read_b64 v[118:119], v228 offset:8
	ds_read_b64 v[120:121], v228 offset:40
	ds_read_b64 v[122:123], v228 offset:72
	ds_read_b64 v[124:125], v228 offset:104
	s_waitcnt lgkmcnt(15)
	v_mfma_f32_16x16x4_f32 v[240:243], v80, v36, 0
	v_mfma_f32_16x16x4_f32 v[240:243], v81, v37, v[240:243]
	v_mfma_f32_16x16x4_f32 v[240:243], v88, v208, v[240:243]
	ds_read_b64 v[186:187], v34
	ds_read_b64 v[190:191], v34 offset:1024
	v_mfma_f32_16x16x4_f32 v[244:247], v89, v209, 0
	ds_read_b64 v[194:195], v34 offset:2048
	ds_read_b64 v[198:199], v34 offset:3072
	v_mfma_f32_16x16x4_f32 v[240:243], v90, v210, v[240:243]
	ds_read_b64 v[184:185], v236
	ds_read_b64 v[188:189], v236 offset:1024
	ds_read_b64 v[132:133], v237 offset:9984
	v_mfma_f32_16x16x4_f32 v[244:247], v91, v211, v[244:247]
	ds_read_b64 v[134:135], v238 offset:9984
	ds_read_b64 v[192:193], v236 offset:2048
	ds_read_b64 v[196:197], v236 offset:3072
	v_mfma_f32_16x16x4_f32 v[240:243], v92, v212, v[240:243]
	ds_read_b32 v38, v239 offset:2048
	ds_read_b32 v39, v239 offset:2304
	ds_read_b128 v[140:143], v225 offset:9984
	v_mfma_f32_16x16x4_f32 v[244:247], v93, v213, v[244:247]
	ds_read_b128 v[144:147], v225 offset:11008
	ds_read_b128 v[148:151], v225 offset:12032
	ds_read_b128 v[152:155], v225 offset:13056
	v_mfma_f32_16x16x4_f32 v[240:243], v94, v214, v[240:243]
	ds_read_b32 v156, v227 offset:9988
	ds_read_b32 v157, v227 offset:10060
	v_mfma_f32_16x16x4_f32 v[244:247], v95, v215, v[244:247]
	ds_read_b64 v[158:159], v227 offset:9992
	ds_read_b64 v[160:161], v227 offset:10024
	v_mfma_f32_16x16x4_f32 v[240:243], v96, v216, v[240:243]
	ds_read_b32 v178, v229 offset:9988
	ds_read_b32 v179, v229 offset:10060
	v_mfma_f32_16x16x4_f32 v[244:247], v97, v217, v[244:247]
	ds_read_b64 v[180:181], v229 offset:9992
	ds_read_b64 v[182:183], v229 offset:10024
	v_mfma_f32_16x16x4_f32 v[240:243], v98, v218, v[240:243]
	ds_read_b64 v[162:163], v228 offset:9984
	ds_read_b64 v[164:165], v228 offset:10016
	v_mfma_f32_16x16x4_f32 v[244:247], v99, v219, v[244:247]
	ds_read_b64 v[166:167], v228 offset:10048
	ds_read_b64 v[168:169], v228 offset:10080
	v_mfma_f32_16x16x4_f32 v[240:243], v100, v220, v[240:243]
	ds_read_b64 v[170:171], v228 offset:9992
	ds_read_b64 v[172:173], v228 offset:10024
	v_mfma_f32_16x16x4_f32 v[244:247], v101, v221, v[244:247]
	ds_read_b64 v[174:175], v228 offset:10056
	ds_read_b64 v[176:177], v228 offset:10088
	v_mfma_f32_16x16x4_f32 v[240:243], v102, v222, v[240:243]
	v_mfma_f32_16x16x4_f32 v[244:247], v103, v223, v[244:247]
	s_waitcnt lgkmcnt(15)
	v_mfma_f32_16x16x4_f32 v[208:211], v186, v36, v[208:211]
	v_mfma_f32_16x16x4_f32 v[212:215], v190, v36, v[212:215]
	v_pk_add_f32 v[240:241], v[240:241], v[244:245]
	v_pk_add_f32 v[242:243], v[242:243], v[246:247]
	v_fmac_f32_e32 v241, v104, v240
	v_mfma_f32_16x16x4_f32 v[216:219], v194, v36, v[216:219]
	v_pk_fma_f32 v[242:243], v[106:107], v[240:241], v[242:243] op_sel:[0,0,0] op_sel_hi:[1,0,1]
	v_pk_fma_f32 v[242:243], v[108:109], v[240:241], v[242:243] op_sel:[0,1,0] op_sel_hi:[1,1,1]
	v_fmac_f32_e32 v243, v105, v242
	v_mfma_f32_16x16x4_f32 v[72:75], v132, v38, 0
	ds_bpermute_b32 v204, v232, v240
	ds_bpermute_b32 v205, v232, v241
	ds_bpermute_b32 v206, v232, v242
	v_mfma_f32_16x16x4_f32 v[72:75], v133, v39, v[72:75]
	ds_bpermute_b32 v207, v232, v243
	s_waitcnt lgkmcnt(2)
	v_pk_fma_f32 v[240:241], v[110:111], v[204:205], v[240:241] op_sel:[0,0,0] op_sel_hi:[1,0,1]
	v_pk_fma_f32 v[240:241], v[112:113], v[204:205], v[240:241] op_sel:[0,1,0] op_sel_hi:[1,1,1]
	v_mfma_f32_16x16x4_f32 v[220:223], v198, v36, v[220:223]
	s_waitcnt lgkmcnt(0)
	v_pk_fma_f32 v[240:241], v[114:115], v[206:207], v[240:241] op_sel:[0,0,0] op_sel_hi:[1,0,1]
	v_pk_fma_f32 v[240:241], v[116:117], v[206:207], v[240:241] op_sel:[0,1,0] op_sel_hi:[1,1,1]
	v_pk_fma_f32 v[242:243], v[118:119], v[204:205], v[242:243] op_sel:[0,0,0] op_sel_hi:[1,0,1]
	v_mfma_f32_16x16x4_f32 v[208:211], v187, v37, v[208:211]
	v_pk_fma_f32 v[242:243], v[120:121], v[204:205], v[242:243] op_sel:[0,1,0] op_sel_hi:[1,1,1]
	v_pk_fma_f32 v[242:243], v[122:123], v[206:207], v[242:243] op_sel:[0,0,0] op_sel_hi:[1,0,1]
	v_pk_fma_f32 v[242:243], v[124:125], v[206:207], v[242:243] op_sel:[0,1,0] op_sel_hi:[1,1,1]
	v_mfma_f32_16x16x4_f32 v[212:215], v191, v37, v[212:215]
	v_fmac_f32_e32 v241, v126, v240
	v_pk_fma_f32 v[242:243], v[128:129], v[240:241], v[242:243] op_sel:[0,0,0] op_sel_hi:[1,0,1]
	v_pk_fma_f32 v[242:243], v[130:131], v[240:241], v[242:243] op_sel:[0,1,0] op_sel_hi:[1,1,1]
	v_mfma_f32_16x16x4_f32 v[216:219], v195, v37, v[216:219]
	v_fmac_f32_e32 v243, v127, v242
	v_mov_b32_e32 v252, v240
	v_mov_b32_e32 v253, v241
	v_mfma_f32_16x16x4_f32 v[220:223], v199, v37, v[220:223]
	v_mov_b32_e32 v254, v242
	v_mov_b32_e32 v255, v243
	s_nop 0
	v_permlane32_swap_b32_e32 v252, v254
	v_permlane32_swap_b32_e32 v253, v255
	s_nop 0
	v_mfma_f32_16x16x4_f32 v[248:251], v82, v252, v[240:243]
	v_mfma_f32_16x16x4_f32 v[248:251], v83, v253, v[248:251]
	v_mfma_f32_16x16x4_f32 v[208:211], v184, v252, v[208:211]
	ds_read_b128 v[88:91], v226
	v_mfma_f32_16x16x4_f32 v[212:215], v188, v252, v[212:215]
	ds_read_b128 v[92:95], v226 offset:64
	v_mfma_f32_16x16x4_f32 v[216:219], v192, v252, v[216:219]
	ds_read_b128 v[96:99], v226 offset:128
	v_mfma_f32_16x16x4_f32 v[220:223], v196, v252, v[220:223]
	ds_read_b128 v[100:103], v226 offset:192
	v_mfma_f32_16x16x4_f32 v[208:211], v185, v253, v[208:211]
	s_mov_b64 exec, s[98:99]
	ds_write_b32 v231, v248
	ds_write_b32 v231, v249 offset:256
	ds_write_b32 v231, v250 offset:512
	ds_write_b32 v231, v251 offset:768
	s_mov_b64 exec, -1
	v_mfma_f32_16x16x4_f32 v[212:215], v189, v253, v[212:215]
	v_mfma_f32_16x16x4_f32 v[216:219], v193, v253, v[216:219]
	v_mfma_f32_16x16x4_f32 v[220:223], v197, v253, v[220:223]
	s_waitcnt lgkmcnt(7)
	v_pk_mul_f32 v[208:209], v[208:209], v[88:89]
	v_pk_mul_f32 v[210:211], v[210:211], v[90:91]
	s_nop 0
	v_mfma_f32_16x16x4_f32 v[72:75], v140, v208, v[72:75]
	s_waitcnt lgkmcnt(6)
	v_pk_mul_f32 v[212:213], v[212:213], v[92:93]
	v_mfma_f32_16x16x4_f32 v[244:247], v141, v209, 0
	v_pk_mul_f32 v[214:215], v[214:215], v[94:95]
	v_mfma_f32_16x16x4_f32 v[72:75], v142, v210, v[72:75]
	s_waitcnt lgkmcnt(5)
	v_pk_mul_f32 v[216:217], v[216:217], v[96:97]
	v_mfma_f32_16x16x4_f32 v[244:247], v143, v211, v[244:247]
	v_pk_mul_f32 v[218:219], v[218:219], v[98:99]
	v_mfma_f32_16x16x4_f32 v[72:75], v144, v212, v[72:75]
	s_waitcnt lgkmcnt(4)
	v_pk_mul_f32 v[220:221], v[220:221], v[100:101]
	v_mfma_f32_16x16x4_f32 v[244:247], v145, v213, v[244:247]
	v_pk_mul_f32 v[222:223], v[222:223], v[102:103]
	v_mfma_f32_16x16x4_f32 v[72:75], v146, v214, v[72:75]
	ds_read_b64 v[186:187], v34 offset:9984
	ds_read_b64 v[190:191], v34 offset:11008
	v_mfma_f32_16x16x4_f32 v[244:247], v147, v215, v[244:247]
	ds_read_b64 v[194:195], v34 offset:12032
	ds_read_b64 v[198:199], v34 offset:13056
	v_mfma_f32_16x16x4_f32 v[72:75], v148, v216, v[72:75]
	ds_read_b64 v[184:185], v236 offset:9984
	ds_read_b64 v[188:189], v236 offset:11008
	ds_read_b64 v[80:81], v32
	v_mfma_f32_16x16x4_f32 v[244:247], v149, v217, v[244:247]
	ds_read_b64 v[82:83], v33
	ds_read_b32 v36, v239 offset:4096
	ds_read_b64 v[192:193], v236 offset:12032
	v_mfma_f32_16x16x4_f32 v[72:75], v150, v218, v[72:75]
	ds_read_b64 v[196:197], v236 offset:13056
	ds_read_b32 v37, v239 offset:4352
	ds_read_b128 v[88:91], v26
	v_mfma_f32_16x16x4_f32 v[244:247], v151, v219, v[244:247]
	ds_read_b128 v[92:95], v26 offset:1024
	ds_read_b128 v[96:99], v26 offset:2048
	ds_read_b128 v[100:103], v26 offset:3072
	v_mfma_f32_16x16x4_f32 v[72:75], v152, v220, v[72:75]
	ds_read_b32 v104, v29 offset:4
	ds_read_b32 v105, v29 offset:76
	ds_read_b64 v[106:107], v29 offset:8
	v_mfma_f32_16x16x4_f32 v[244:247], v153, v221, v[244:247]
	ds_read_b64 v[108:109], v29 offset:40
	ds_read_b32 v126, v31 offset:4
	ds_read_b32 v127, v31 offset:76
	v_mfma_f32_16x16x4_f32 v[72:75], v154, v222, v[72:75]
	ds_read_b64 v[128:129], v31 offset:8
	ds_read_b64 v[130:131], v31 offset:40
	ds_read_b64 v[110:111], v30
	v_mfma_f32_16x16x4_f32 v[244:247], v155, v223, v[244:247]
	ds_read_b64 v[112:113], v30 offset:32
	ds_read_b64 v[114:115], v30 offset:64
	ds_read_b64 v[116:117], v30 offset:96
	ds_read_b64 v[118:119], v30 offset:8
	ds_read_b64 v[120:121], v30 offset:40
	ds_read_b64 v[122:123], v30 offset:72
	ds_read_b64 v[124:125], v30 offset:104
	s_waitcnt lgkmcnt(15)
	v_mfma_f32_16x16x4_f32 v[208:211], v186, v38, v[208:211]
	v_mfma_f32_16x16x4_f32 v[212:215], v190, v38, v[212:215]
	v_pk_add_f32 v[72:73], v[72:73], v[244:245]
	v_pk_add_f32 v[74:75], v[74:75], v[246:247]
	v_fmac_f32_e32 v73, v156, v72
	v_mfma_f32_16x16x4_f32 v[216:219], v194, v38, v[216:219]
	v_pk_fma_f32 v[74:75], v[158:159], v[72:73], v[74:75] op_sel:[0,0,0] op_sel_hi:[1,0,1]
	v_pk_fma_f32 v[74:75], v[160:161], v[72:73], v[74:75] op_sel:[0,1,0] op_sel_hi:[1,1,1]
	v_fmac_f32_e32 v75, v157, v74
	v_mfma_f32_16x16x4_f32 v[240:243], v80, v36, 0
	ds_bpermute_b32 v204, v232, v72
	ds_bpermute_b32 v205, v232, v73
	ds_bpermute_b32 v206, v232, v74
	v_mfma_f32_16x16x4_f32 v[240:243], v81, v37, v[240:243]
	ds_bpermute_b32 v207, v232, v75
	s_waitcnt lgkmcnt(2)
	v_pk_fma_f32 v[72:73], v[162:163], v[204:205], v[72:73] op_sel:[0,0,0] op_sel_hi:[1,0,1]
	v_pk_fma_f32 v[72:73], v[164:165], v[204:205], v[72:73] op_sel:[0,1,0] op_sel_hi:[1,1,1]
	v_mfma_f32_16x16x4_f32 v[220:223], v198, v38, v[220:223]
	s_waitcnt lgkmcnt(0)
	v_pk_fma_f32 v[72:73], v[166:167], v[206:207], v[72:73] op_sel:[0,0,0] op_sel_hi:[1,0,1]
	v_pk_fma_f32 v[72:73], v[168:169], v[206:207], v[72:73] op_sel:[0,1,0] op_sel_hi:[1,1,1]
	v_pk_fma_f32 v[74:75], v[170:171], v[204:205], v[74:75] op_sel:[0,0,0] op_sel_hi:[1,0,1]
	v_mfma_f32_16x16x4_f32 v[208:211], v187, v39, v[208:211]
	v_pk_fma_f32 v[74:75], v[172:173], v[204:205], v[74:75] op_sel:[0,1,0] op_sel_hi:[1,1,1]
	v_pk_fma_f32 v[74:75], v[174:175], v[206:207], v[74:75] op_sel:[0,0,0] op_sel_hi:[1,0,1]
	v_pk_fma_f32 v[74:75], v[176:177], v[206:207], v[74:75] op_sel:[0,1,0] op_sel_hi:[1,1,1]
	v_mfma_f32_16x16x4_f32 v[212:215], v191, v39, v[212:215]
	v_fmac_f32_e32 v73, v178, v72
	v_pk_fma_f32 v[74:75], v[180:181], v[72:73], v[74:75] op_sel:[0,0,0] op_sel_hi:[1,0,1]
	v_pk_fma_f32 v[74:75], v[182:183], v[72:73], v[74:75] op_sel:[0,1,0] op_sel_hi:[1,1,1]
	v_mfma_f32_16x16x4_f32 v[216:219], v195, v39, v[216:219]
	v_fmac_f32_e32 v75, v179, v74
	v_mov_b32_e32 v252, v72
	v_mov_b32_e32 v253, v73
	v_mfma_f32_16x16x4_f32 v[220:223], v199, v39, v[220:223]
	v_mov_b32_e32 v254, v74
	v_mov_b32_e32 v255, v75
	s_nop 0
	v_permlane32_swap_b32_e32 v252, v254
	v_permlane32_swap_b32_e32 v253, v255
	s_nop 0
	v_mfma_f32_16x16x4_f32 v[248:251], v134, v252, v[72:75]
	v_mfma_f32_16x16x4_f32 v[248:251], v135, v253, v[248:251]
	v_mfma_f32_16x16x4_f32 v[208:211], v184, v252, v[208:211]
	ds_read_b128 v[140:143], v226 offset:9984
	v_mfma_f32_16x16x4_f32 v[212:215], v188, v252, v[212:215]
	ds_read_b128 v[144:147], v226 offset:10048
	v_mfma_f32_16x16x4_f32 v[216:219], v192, v252, v[216:219]
	ds_read_b128 v[148:151], v226 offset:10112
	v_mfma_f32_16x16x4_f32 v[220:223], v196, v252, v[220:223]
	ds_read_b128 v[152:155], v226 offset:10176
	v_mfma_f32_16x16x4_f32 v[208:211], v185, v253, v[208:211]
	s_mov_b64 exec, s[98:99]
	ds_write_b32 v231, v248 offset:2048
	ds_write_b32 v231, v249 offset:2304
	ds_write_b32 v231, v250 offset:2560
	ds_write_b32 v231, v251 offset:2816
	s_mov_b64 exec, -1
	v_mfma_f32_16x16x4_f32 v[212:215], v189, v253, v[212:215]
	v_mfma_f32_16x16x4_f32 v[216:219], v193, v253, v[216:219]
	v_mfma_f32_16x16x4_f32 v[220:223], v197, v253, v[220:223]
	s_waitcnt lgkmcnt(7)
	v_pk_mul_f32 v[208:209], v[208:209], v[140:141]
	v_pk_mul_f32 v[210:211], v[210:211], v[142:143]
	s_nop 0
	v_mfma_f32_16x16x4_f32 v[240:243], v88, v208, v[240:243]
	s_waitcnt lgkmcnt(6)
	v_pk_mul_f32 v[212:213], v[212:213], v[144:145]
	v_mfma_f32_16x16x4_f32 v[244:247], v89, v209, 0
	v_pk_mul_f32 v[214:215], v[214:215], v[146:147]
	v_mfma_f32_16x16x4_f32 v[240:243], v90, v210, v[240:243]
	s_waitcnt lgkmcnt(5)
	v_pk_mul_f32 v[216:217], v[216:217], v[148:149]
	v_mfma_f32_16x16x4_f32 v[244:247], v91, v211, v[244:247]
	v_pk_mul_f32 v[218:219], v[218:219], v[150:151]
	v_mfma_f32_16x16x4_f32 v[240:243], v92, v212, v[240:243]
	s_waitcnt lgkmcnt(4)
	v_pk_mul_f32 v[220:221], v[220:221], v[152:153]
	v_mfma_f32_16x16x4_f32 v[244:247], v93, v213, v[244:247]
	v_pk_mul_f32 v[222:223], v[222:223], v[154:155]
	v_mfma_f32_16x16x4_f32 v[240:243], v94, v214, v[240:243]
	ds_read_b64 v[186:187], v35
	ds_read_b64 v[190:191], v35 offset:1024
	v_mfma_f32_16x16x4_f32 v[244:247], v95, v215, v[244:247]
	ds_read_b64 v[194:195], v35 offset:2048
	ds_read_b64 v[198:199], v35 offset:3072
	v_mfma_f32_16x16x4_f32 v[240:243], v96, v216, v[240:243]
	ds_read_b64 v[184:185], v27
	ds_read_b64 v[188:189], v27 offset:1024
	ds_read_b64 v[132:133], v32 offset:9984
	v_mfma_f32_16x16x4_f32 v[244:247], v97, v217, v[244:247]
	ds_read_b64 v[134:135], v33 offset:9984
	ds_read_b32 v38, v239 offset:6144
	ds_read_b64 v[192:193], v27 offset:2048
	v_mfma_f32_16x16x4_f32 v[240:243], v98, v218, v[240:243]
	ds_read_b64 v[196:197], v27 offset:3072
	ds_read_b32 v39, v239 offset:6400
	ds_read_b128 v[140:143], v26 offset:9984
	v_mfma_f32_16x16x4_f32 v[244:247], v99, v219, v[244:247]
	ds_read_b128 v[144:147], v26 offset:11008
	ds_read_b128 v[148:151], v26 offset:12032
	ds_read_b128 v[152:155], v26 offset:13056
	v_mfma_f32_16x16x4_f32 v[240:243], v100, v220, v[240:243]
	ds_read_b32 v156, v29 offset:9988
	ds_read_b32 v157, v29 offset:10060
	ds_read_b64 v[158:159], v29 offset:9992
	v_mfma_f32_16x16x4_f32 v[244:247], v101, v221, v[244:247]
	ds_read_b64 v[160:161], v29 offset:10024
	ds_read_b32 v178, v31 offset:9988
	ds_read_b32 v179, v31 offset:10060
	v_mfma_f32_16x16x4_f32 v[240:243], v102, v222, v[240:243]
	ds_read_b64 v[180:181], v31 offset:9992
	ds_read_b64 v[182:183], v31 offset:10024
	ds_read_b64 v[162:163], v30 offset:9984
	v_mfma_f32_16x16x4_f32 v[244:247], v103, v223, v[244:247]
	ds_read_b64 v[164:165], v30 offset:10016
	ds_read_b64 v[166:167], v30 offset:10048
	ds_read_b64 v[168:169], v30 offset:10080
	ds_read_b64 v[170:171], v30 offset:9992
	ds_read_b64 v[172:173], v30 offset:10024
	ds_read_b64 v[174:175], v30 offset:10056
	ds_read_b64 v[176:177], v30 offset:10088
	s_waitcnt lgkmcnt(15)
	v_mfma_f32_16x16x4_f32 v[208:211], v186, v36, v[208:211]
	v_mfma_f32_16x16x4_f32 v[212:215], v190, v36, v[212:215]
	v_pk_add_f32 v[240:241], v[240:241], v[244:245]
	v_pk_add_f32 v[242:243], v[242:243], v[246:247]
	v_fmac_f32_e32 v241, v104, v240
	v_mfma_f32_16x16x4_f32 v[216:219], v194, v36, v[216:219]
	v_pk_fma_f32 v[242:243], v[106:107], v[240:241], v[242:243] op_sel:[0,0,0] op_sel_hi:[1,0,1]
	v_pk_fma_f32 v[242:243], v[108:109], v[240:241], v[242:243] op_sel:[0,1,0] op_sel_hi:[1,1,1]
	v_fmac_f32_e32 v243, v105, v242
	v_mfma_f32_16x16x4_f32 v[72:75], v132, v38, 0
	ds_bpermute_b32 v204, v232, v240
	ds_bpermute_b32 v205, v232, v241
	ds_bpermute_b32 v206, v232, v242
	v_mfma_f32_16x16x4_f32 v[72:75], v133, v39, v[72:75]
	ds_bpermute_b32 v207, v232, v243
	s_waitcnt lgkmcnt(2)
	v_pk_fma_f32 v[240:241], v[110:111], v[204:205], v[240:241] op_sel:[0,0,0] op_sel_hi:[1,0,1]
	v_pk_fma_f32 v[240:241], v[112:113], v[204:205], v[240:241] op_sel:[0,1,0] op_sel_hi:[1,1,1]
	v_mfma_f32_16x16x4_f32 v[220:223], v198, v36, v[220:223]
	s_waitcnt lgkmcnt(0)
	v_pk_fma_f32 v[240:241], v[114:115], v[206:207], v[240:241] op_sel:[0,0,0] op_sel_hi:[1,0,1]
	v_pk_fma_f32 v[240:241], v[116:117], v[206:207], v[240:241] op_sel:[0,1,0] op_sel_hi:[1,1,1]
	v_pk_fma_f32 v[242:243], v[118:119], v[204:205], v[242:243] op_sel:[0,0,0] op_sel_hi:[1,0,1]
	v_mfma_f32_16x16x4_f32 v[208:211], v187, v37, v[208:211]
	v_pk_fma_f32 v[242:243], v[120:121], v[204:205], v[242:243] op_sel:[0,1,0] op_sel_hi:[1,1,1]
	v_pk_fma_f32 v[242:243], v[122:123], v[206:207], v[242:243] op_sel:[0,0,0] op_sel_hi:[1,0,1]
	v_pk_fma_f32 v[242:243], v[124:125], v[206:207], v[242:243] op_sel:[0,1,0] op_sel_hi:[1,1,1]
	v_mfma_f32_16x16x4_f32 v[212:215], v191, v37, v[212:215]
	v_fmac_f32_e32 v241, v126, v240
	v_pk_fma_f32 v[242:243], v[128:129], v[240:241], v[242:243] op_sel:[0,0,0] op_sel_hi:[1,0,1]
	v_pk_fma_f32 v[242:243], v[130:131], v[240:241], v[242:243] op_sel:[0,1,0] op_sel_hi:[1,1,1]
	v_mfma_f32_16x16x4_f32 v[216:219], v195, v37, v[216:219]
	v_fmac_f32_e32 v243, v127, v242
	v_mov_b32_e32 v252, v240
	v_mov_b32_e32 v253, v241
	v_mfma_f32_16x16x4_f32 v[220:223], v199, v37, v[220:223]
	v_mov_b32_e32 v254, v242
	v_mov_b32_e32 v255, v243
	s_nop 0
	v_permlane32_swap_b32_e32 v252, v254
	v_permlane32_swap_b32_e32 v253, v255
	s_nop 0
	v_mfma_f32_16x16x4_f32 v[248:251], v82, v252, v[240:243]
	v_mfma_f32_16x16x4_f32 v[248:251], v83, v253, v[248:251]
	v_mfma_f32_16x16x4_f32 v[208:211], v184, v252, v[208:211]
	ds_read_b128 v[88:91], v28
	v_mfma_f32_16x16x4_f32 v[212:215], v188, v252, v[212:215]
	ds_read_b128 v[92:95], v28 offset:64
	v_mfma_f32_16x16x4_f32 v[216:219], v192, v252, v[216:219]
	ds_read_b128 v[96:99], v28 offset:128
	v_mfma_f32_16x16x4_f32 v[220:223], v196, v252, v[220:223]
	ds_read_b128 v[100:103], v28 offset:192
	v_mfma_f32_16x16x4_f32 v[208:211], v185, v253, v[208:211]
	s_mov_b64 exec, s[98:99]
	ds_write_b32 v231, v248 offset:4096
	ds_write_b32 v231, v249 offset:4352
	ds_write_b32 v231, v250 offset:4608
	ds_write_b32 v231, v251 offset:4864
	s_mov_b64 exec, -1
	v_mfma_f32_16x16x4_f32 v[212:215], v189, v253, v[212:215]
	v_mfma_f32_16x16x4_f32 v[216:219], v193, v253, v[216:219]
	v_mfma_f32_16x16x4_f32 v[220:223], v197, v253, v[220:223]
	s_waitcnt lgkmcnt(7)
	v_pk_mul_f32 v[208:209], v[208:209], v[88:89]
	v_pk_mul_f32 v[210:211], v[210:211], v[90:91]
	s_nop 0
	v_mfma_f32_16x16x4_f32 v[72:75], v140, v208, v[72:75]
	s_waitcnt lgkmcnt(6)
	v_pk_mul_f32 v[212:213], v[212:213], v[92:93]
	v_mfma_f32_16x16x4_f32 v[244:247], v141, v209, 0
	v_pk_mul_f32 v[214:215], v[214:215], v[94:95]
	v_mfma_f32_16x16x4_f32 v[72:75], v142, v210, v[72:75]
	s_waitcnt lgkmcnt(5)
	v_pk_mul_f32 v[216:217], v[216:217], v[96:97]
	v_mfma_f32_16x16x4_f32 v[244:247], v143, v211, v[244:247]
	v_pk_mul_f32 v[218:219], v[218:219], v[98:99]
	v_mfma_f32_16x16x4_f32 v[72:75], v144, v212, v[72:75]
	s_waitcnt lgkmcnt(4)
	v_pk_mul_f32 v[220:221], v[220:221], v[100:101]
	v_mfma_f32_16x16x4_f32 v[244:247], v145, v213, v[244:247]
	v_pk_mul_f32 v[222:223], v[222:223], v[102:103]
	v_mfma_f32_16x16x4_f32 v[72:75], v146, v214, v[72:75]
	ds_read_b64 v[186:187], v35 offset:9984
	ds_read_b64 v[190:191], v35 offset:11008
	v_mfma_f32_16x16x4_f32 v[244:247], v147, v215, v[244:247]
	ds_read_b64 v[194:195], v35 offset:12032
	ds_read_b64 v[198:199], v35 offset:13056
	v_mfma_f32_16x16x4_f32 v[72:75], v148, v216, v[72:75]
	ds_read_b64 v[184:185], v27 offset:9984
	ds_read_b64 v[188:189], v27 offset:11008
	v_mfma_f32_16x16x4_f32 v[244:247], v149, v217, v[244:247]
	ds_read_b64 v[192:193], v27 offset:12032
	ds_read_b64 v[196:197], v27 offset:13056
	v_mfma_f32_16x16x4_f32 v[72:75], v150, v218, v[72:75]
	v_mfma_f32_16x16x4_f32 v[244:247], v151, v219, v[244:247]
	v_mfma_f32_16x16x4_f32 v[72:75], v152, v220, v[72:75]
	v_mfma_f32_16x16x4_f32 v[244:247], v153, v221, v[244:247]
	v_mfma_f32_16x16x4_f32 v[72:75], v154, v222, v[72:75]
	v_mfma_f32_16x16x4_f32 v[244:247], v155, v223, v[244:247]
	s_waitcnt lgkmcnt(7)
	v_mfma_f32_16x16x4_f32 v[208:211], v186, v38, v[208:211]
	s_waitcnt lgkmcnt(6)
	v_mfma_f32_16x16x4_f32 v[212:215], v190, v38, v[212:215]
	v_pk_add_f32 v[72:73], v[72:73], v[244:245]
	v_pk_add_f32 v[74:75], v[74:75], v[246:247]
	v_fmac_f32_e32 v73, v156, v72
	s_waitcnt lgkmcnt(5)
	v_mfma_f32_16x16x4_f32 v[216:219], v194, v38, v[216:219]
	v_pk_fma_f32 v[74:75], v[158:159], v[72:73], v[74:75] op_sel:[0,0,0] op_sel_hi:[1,0,1]
	v_pk_fma_f32 v[74:75], v[160:161], v[72:73], v[74:75] op_sel:[0,1,0] op_sel_hi:[1,1,1]
	v_fmac_f32_e32 v75, v157, v74
	s_waitcnt lgkmcnt(4)
	v_mfma_f32_16x16x4_f32 v[220:223], v198, v38, v[220:223]
	ds_bpermute_b32 v204, v232, v72
	ds_bpermute_b32 v205, v232, v73
	ds_bpermute_b32 v206, v232, v74
	v_mfma_f32_16x16x4_f32 v[208:211], v187, v39, v[208:211]
	ds_bpermute_b32 v207, v232, v75
	s_waitcnt lgkmcnt(2)
	v_pk_fma_f32 v[72:73], v[162:163], v[204:205], v[72:73] op_sel:[0,0,0] op_sel_hi:[1,0,1]
	v_pk_fma_f32 v[72:73], v[164:165], v[204:205], v[72:73] op_sel:[0,1,0] op_sel_hi:[1,1,1]
	v_mfma_f32_16x16x4_f32 v[212:215], v191, v39, v[212:215]
	s_waitcnt lgkmcnt(0)
	v_pk_fma_f32 v[72:73], v[166:167], v[206:207], v[72:73] op_sel:[0,0,0] op_sel_hi:[1,0,1]
	v_pk_fma_f32 v[72:73], v[168:169], v[206:207], v[72:73] op_sel:[0,1,0] op_sel_hi:[1,1,1]
	v_pk_fma_f32 v[74:75], v[170:171], v[204:205], v[74:75] op_sel:[0,0,0] op_sel_hi:[1,0,1]
	v_mfma_f32_16x16x4_f32 v[216:219], v195, v39, v[216:219]
	v_pk_fma_f32 v[74:75], v[172:173], v[204:205], v[74:75] op_sel:[0,1,0] op_sel_hi:[1,1,1]
	v_pk_fma_f32 v[74:75], v[174:175], v[206:207], v[74:75] op_sel:[0,0,0] op_sel_hi:[1,0,1]
	v_pk_fma_f32 v[74:75], v[176:177], v[206:207], v[74:75] op_sel:[0,1,0] op_sel_hi:[1,1,1]
	v_mfma_f32_16x16x4_f32 v[220:223], v199, v39, v[220:223]
	v_fmac_f32_e32 v73, v178, v72
	v_pk_fma_f32 v[74:75], v[180:181], v[72:73], v[74:75] op_sel:[0,0,0] op_sel_hi:[1,0,1]
	v_pk_fma_f32 v[74:75], v[182:183], v[72:73], v[74:75] op_sel:[0,1,0] op_sel_hi:[1,1,1]
	v_fmac_f32_e32 v75, v179, v74
	v_mov_b32_e32 v252, v72
	v_mov_b32_e32 v253, v73
	v_mov_b32_e32 v254, v74
	v_mov_b32_e32 v255, v75
	s_nop 0
	v_permlane32_swap_b32_e32 v252, v254
	v_permlane32_swap_b32_e32 v253, v255
	s_nop 0
	v_mfma_f32_16x16x4_f32 v[248:251], v134, v252, v[72:75]
	v_mfma_f32_16x16x4_f32 v[248:251], v135, v253, v[248:251]
	v_mfma_f32_16x16x4_f32 v[208:211], v184, v252, v[208:211]
	ds_read_b128 v[140:143], v28 offset:9984
	v_mfma_f32_16x16x4_f32 v[212:215], v188, v252, v[212:215]
	ds_read_b128 v[144:147], v28 offset:10048
	v_mfma_f32_16x16x4_f32 v[216:219], v192, v252, v[216:219]
	ds_read_b128 v[148:151], v28 offset:10112
	v_mfma_f32_16x16x4_f32 v[220:223], v196, v252, v[220:223]
	ds_read_b128 v[152:155], v28 offset:10176
	v_mfma_f32_16x16x4_f32 v[208:211], v185, v253, v[208:211]
	s_mov_b64 exec, s[98:99]
	ds_write_b32 v231, v248 offset:6144
	ds_write_b32 v231, v249 offset:6400
	ds_write_b32 v231, v250 offset:6656
	ds_write_b32 v231, v251 offset:6912
	s_mov_b64 exec, -1
	v_mfma_f32_16x16x4_f32 v[212:215], v189, v253, v[212:215]
	v_mfma_f32_16x16x4_f32 v[216:219], v193, v253, v[216:219]
	v_mfma_f32_16x16x4_f32 v[220:223], v197, v253, v[220:223]
	s_waitcnt lgkmcnt(7)
	v_pk_mul_f32 v[208:209], v[208:209], v[140:141]
	v_pk_mul_f32 v[210:211], v[210:211], v[142:143]
	s_waitcnt lgkmcnt(6)
	v_pk_mul_f32 v[212:213], v[212:213], v[144:145]
	v_pk_mul_f32 v[214:215], v[214:215], v[146:147]
	s_waitcnt lgkmcnt(5)
	v_pk_mul_f32 v[216:217], v[216:217], v[148:149]
	v_pk_mul_f32 v[218:219], v[218:219], v[150:151]
	s_waitcnt lgkmcnt(4)
	s_nop 3
	v_pk_mul_f32 v[220:221], v[220:221], v[152:153]
	v_pk_mul_f32 v[222:223], v[222:223], v[154:155]
	s_branch .LBB0_655

.Lmy_f_nol34:
	s_waitcnt lgkmcnt(0)
	s_bfe_u32 s96, s62, 0x20006
	s_and_b32 s97, s96, 1
	s_mul_i32 s97, s97, 0x2700
	s_mov_b32 s101, 0x1c000
	s_mov_b32 s100, 0x6100
	s_bitcmp0_b32 s65, 0
	s_cselect_b32 s101, 0xe000, s101
	s_cselect_b32 s100, 0x4e00, s100
	s_cmp_gt_u32 s96, 1
	s_cselect_b32 s100, s100, 0
	s_add_i32 s97, s97, s101
	s_add_i32 s97, s97, s100
	ds_read_b32 v80, v198
	ds_read_b32 v81, v198 offset:256
	ds_read_b32 v82, v198 offset:512
	ds_read_b32 v83, v198 offset:768
	ds_read_b32 v84, v198 offset:1024
	ds_read_b32 v85, v198 offset:1280
	ds_read_b32 v86, v198 offset:1536
	ds_read_b32 v87, v198 offset:1792
	ds_read_b32 v88, v198 offset:8192
	ds_read_b32 v89, v198 offset:8448
	ds_read_b32 v90, v198 offset:8704
	ds_read_b32 v91, v198 offset:8960
	ds_read_b32 v92, v198 offset:9216
	ds_read_b32 v93, v198 offset:9472
	ds_read_b32 v94, v198 offset:9728
	ds_read_b32 v95, v198 offset:9984
	ds_read_b32 v96, v198 offset:32768
	ds_read_b32 v97, v198 offset:33024
	ds_read_b32 v98, v198 offset:33280
	ds_read_b32 v99, v198 offset:33536
	ds_read_b32 v100, v198 offset:33792
	ds_read_b32 v101, v198 offset:34048
	ds_read_b32 v102, v198 offset:34304
	ds_read_b32 v103, v198 offset:34560
	s_add_i32 s100, s97, 0x0
	v_add_u32_e32 v76, s100, v200
	v_add_u32_e32 v77, s100, v201
	v_add_u32_e32 v78, s100, v202
	v_add_u32_e32 v79, s100, v203
	s_waitcnt lgkmcnt(15)
	v_mov_b32_e32 v104, v80
	v_mul_f32_e32 v105, v104, v81
	v_mul_f32_e32 v106, v105, v82
	v_mul_f32_e32 v107, v106, v83
	v_mul_f32_e32 v108, v107, v84
	v_mul_f32_e32 v109, v108, v85
	v_mul_f32_e32 v110, v109, v86
	v_mul_f32_e32 v111, v110, v87
	v_mov_b32_e32 v112, v88
	s_waitcnt lgkmcnt(14)
	v_mul_f32_e32 v113, v104, v89
	s_waitcnt lgkmcnt(13)
	v_mul_f32_e32 v114, v105, v90
	s_waitcnt lgkmcnt(12)
	v_mul_f32_e32 v115, v106, v91
	s_waitcnt lgkmcnt(11)
	v_mul_f32_e32 v116, v107, v92
	s_waitcnt lgkmcnt(10)
	v_mul_f32_e32 v117, v108, v93
	s_waitcnt lgkmcnt(9)
	v_mul_f32_e32 v118, v109, v94
	s_waitcnt lgkmcnt(8)
	v_mul_f32_e32 v119, v110, v95
	s_waitcnt lgkmcnt(7)
	v_mul_f32_e32 v120, v104, v96
	s_waitcnt lgkmcnt(6)
	v_mul_f32_e32 v121, v105, v97
	s_waitcnt lgkmcnt(5)
	v_mul_f32_e32 v122, v106, v98
	s_waitcnt lgkmcnt(4)
	v_mul_f32_e32 v123, v107, v99
	s_waitcnt lgkmcnt(3)
	v_mul_f32_e32 v124, v108, v100
	s_waitcnt lgkmcnt(2)
	v_mul_f32_e32 v125, v109, v101
	s_waitcnt lgkmcnt(1)
	v_mul_f32_e32 v126, v110, v102
	s_waitcnt lgkmcnt(0)
	v_mul_f32_e32 v127, v111, v103
	ds_write_b32 v76, v112
	ds_write_b32 v77, v113
	ds_write_b32 v78, v114
	ds_write_b32 v79, v115
	ds_write_b32 v76, v116 offset:64
	ds_write_b32 v77, v117 offset:64
	ds_write_b32 v78, v118 offset:64
	ds_write_b32 v79, v119 offset:64
	ds_write_b32 v76, v120 offset:128
	ds_write_b32 v77, v121 offset:128
	ds_write_b32 v78, v122 offset:128
	ds_write_b32 v79, v123 offset:128
	ds_write_b32 v76, v124 offset:192
	ds_write_b32 v77, v125 offset:192
	ds_write_b32 v78, v126 offset:192
	ds_write_b32 v79, v127 offset:192
	s_waitcnt lgkmcnt(0)
	ds_read_b32 v88, v198 offset:16384
	ds_read_b32 v89, v198 offset:16640
	ds_read_b32 v90, v198 offset:16896
	ds_read_b32 v91, v198 offset:17152
	ds_read_b32 v92, v198 offset:17408
	ds_read_b32 v93, v198 offset:17664
	ds_read_b32 v94, v198 offset:17920
	ds_read_b32 v95, v198 offset:18176
	ds_read_b32 v96, v198 offset:24576
	ds_read_b32 v97, v198 offset:24832
	ds_read_b32 v98, v198 offset:25088
	ds_read_b32 v99, v198 offset:25344
	ds_read_b32 v100, v198 offset:25600
	ds_read_b32 v101, v198 offset:25856
	ds_read_b32 v102, v198 offset:26112
	ds_read_b32 v103, v198 offset:26368
	s_add_i32 s101, s97, 0x1000
	v_add_u32_e32 v74, s101, v204
	s_add_i32 s101, s97, 0x2000
	v_add_u32_e32 v75, s101, v205
	v_rcp_f32_e32 v112, v104
	v_rcp_f32_e32 v113, v105
	v_rcp_f32_e32 v114, v106
	v_rcp_f32_e32 v115, v107
	v_rcp_f32_e32 v116, v108
	v_rcp_f32_e32 v117, v109
	v_rcp_f32_e32 v118, v110
	v_rcp_f32_e32 v119, v111
	s_waitcnt lgkmcnt(7)
	v_mul_f32_e32 v120, v112, v96
	s_waitcnt lgkmcnt(6)
	v_mul_f32_e32 v121, v113, v97
	s_waitcnt lgkmcnt(5)
	v_mul_f32_e32 v122, v114, v98
	s_waitcnt lgkmcnt(4)
	v_mul_f32_e32 v123, v115, v99
	s_waitcnt lgkmcnt(3)
	v_mul_f32_e32 v124, v116, v100
	s_waitcnt lgkmcnt(2)
	v_mul_f32_e32 v125, v117, v101
	s_waitcnt lgkmcnt(1)
	v_mul_f32_e32 v126, v118, v102
	s_waitcnt lgkmcnt(0)
	v_mul_f32_e32 v127, v119, v103
	v_mul_f32_e32 v112, v112, v88
	v_mul_f32_e32 v113, v113, v89
	v_mul_f32_e32 v114, v114, v90
	v_mul_f32_e32 v115, v115, v91
	v_mul_f32_e32 v116, v116, v92
	v_mul_f32_e32 v117, v117, v93
	v_mul_f32_e32 v118, v118, v94
	v_mul_f32_e32 v119, v119, v95
	ds_write_b128 v74, v[112:115]
	ds_write_b128 v74, v[116:119] offset:256
	ds_write_b128 v74, v[120:123] offset:512
	ds_write_b128 v74, v[124:127] offset:768
	ds_write_b32 v75, v111
	s_waitcnt lgkmcnt(0)
	s_bfe_u32 s96, s62, 0x20006
	s_and_b32 s97, s96, 1
	s_mul_i32 s97, s97, 0x2700
	s_mov_b32 s101, 0x1c000
	s_mov_b32 s100, 0x6100
	s_bitcmp0_b32 s65, 0
	s_cselect_b32 s101, 0xe000, s101
	s_cselect_b32 s100, 0x4e00, s100
	s_cmp_gt_u32 s96, 1
	s_cselect_b32 s100, s100, 0
	s_add_i32 s97, s97, s101
	s_add_i32 s97, s97, s100
	s_mov_b32 s96, s97
	s_add_i32 s101, s96, 0x1000
	v_add_u32_e32 v78, s101, v206
	v_add_u32_e32 v79, s96, v207
	ds_read_b128 v[96:99], v79
	ds_read_b128 v[100:103], v79 offset:1024
	ds_read_b128 v[104:107], v79 offset:2048
	ds_read_b128 v[108:111], v79 offset:3072
	ds_read_b32 v80, v78
	ds_read_b32 v81, v78 offset:16
	ds_read_b32 v82, v78 offset:32
	ds_read_b32 v83, v78 offset:48
	ds_read_b32 v84, v78 offset:1024
	ds_read_b32 v85, v78 offset:1040
	ds_read_b32 v86, v78 offset:1056
	ds_read_b32 v87, v78 offset:1072
	ds_read_b32 v88, v78 offset:2048
	ds_read_b32 v89, v78 offset:2064
	ds_read_b32 v90, v78 offset:2080
	ds_read_b32 v91, v78 offset:2096
	ds_read_b32 v92, v78 offset:3072
	ds_read_b32 v93, v78 offset:3088
	ds_read_b32 v94, v78 offset:3104
	ds_read_b32 v95, v78 offset:3120
	v_add_u32_e32 v74, s96, v205
	ds_write_b32 v74, v235 offset:9728
	s_waitcnt lgkmcnt(15)
	v_mfma_f32_16x16x4_f32 v[244:247], v80, v96, 0
	v_mfma_f32_16x16x4_f32 v[240:243], v81, v97, 0
	s_waitcnt lgkmcnt(14)
	v_mfma_f32_16x16x4_f32 v[244:247], v82, v98, v[244:247]
	s_waitcnt lgkmcnt(13)
	v_mfma_f32_16x16x4_f32 v[240:243], v83, v99, v[240:243]
	s_waitcnt lgkmcnt(12)
	v_mfma_f32_16x16x4_f32 v[244:247], v84, v100, v[244:247]
	s_waitcnt lgkmcnt(11)
	v_mfma_f32_16x16x4_f32 v[240:243], v85, v101, v[240:243]
	s_waitcnt lgkmcnt(10)
	v_mfma_f32_16x16x4_f32 v[244:247], v86, v102, v[244:247]
	s_waitcnt lgkmcnt(9)
	v_mfma_f32_16x16x4_f32 v[240:243], v87, v103, v[240:243]
	s_waitcnt lgkmcnt(8)
	v_mfma_f32_16x16x4_f32 v[244:247], v88, v104, v[244:247]
	s_waitcnt lgkmcnt(7)
	v_mfma_f32_16x16x4_f32 v[240:243], v89, v105, v[240:243]
	s_waitcnt lgkmcnt(6)
	v_mfma_f32_16x16x4_f32 v[244:247], v90, v106, v[244:247]
	s_waitcnt lgkmcnt(5)
	v_mfma_f32_16x16x4_f32 v[240:243], v91, v107, v[240:243]
	s_waitcnt lgkmcnt(4)
	v_mfma_f32_16x16x4_f32 v[244:247], v92, v108, v[244:247]
	s_waitcnt lgkmcnt(3)
	v_mfma_f32_16x16x4_f32 v[240:243], v93, v109, v[240:243]
	s_waitcnt lgkmcnt(2)
	v_mfma_f32_16x16x4_f32 v[244:247], v94, v110, v[244:247]
	s_waitcnt lgkmcnt(1)
	v_mfma_f32_16x16x4_f32 v[240:243], v95, v111, v[240:243]
	s_nop 9
	v_add_f32_e32 v244, v244, v240
	v_add_f32_e32 v245, v245, v241
	v_add_f32_e32 v246, v246, v242
	v_add_f32_e32 v247, v247, v243
	v_mul_f32_e32 v128, v244, v208
	v_mul_f32_e32 v129, v245, v209
	v_mul_f32_e32 v130, v246, v210
	v_mul_f32_e32 v131, v247, v211
	ds_write_b128 v79, v[128:131] offset:8448
	v_add_u32_e32 v75, s96, v216
	v_mul_f32_e32 v132, v244, v212
	v_mul_f32_e32 v133, v245, v213
	v_mul_f32_e32 v134, v246, v214
	v_mul_f32_e32 v135, v247, v215
	s_mov_b64 exec, 0x00ff00ff
	ds_write_b32 v75, v132 offset:9472
	ds_write_b32 v75, v133 offset:9504
	ds_write_b32 v75, v134 offset:9536
	ds_write_b32 v75, v135 offset:9568
	s_mov_b64 exec, -1
	s_setprio 0
	s_branch .LBB0_655
	s_nop 0
	s_nop 0
	s_nop 0
	s_nop 0
	s_nop 0
